# GEMM main loops: LDS-DMA loads addressed as SGPR tile base + 32-bit lane offset (+ immediate, M0 compensated) instead of a 64-bit VALU add per load
# speedup vs baseline: 1.0126x; 1.0026x over previous
.LBB0_631:
	s_add_u32 s22, s88, 0xfff80080
	s_addc_u32 s23, s89, -1
	s_add_i32 s44, 0, 0x10000
	s_cmp_eq_u32 s43, 28
	s_cselect_b32 s23, s30, s23
	s_cselect_b32 s22, s31, s22
	s_cselect_b32 s91, s38, s42
	s_cselect_b32 s90, s39, s41
	s_add_i32 s81, 0, 0x14000
	v_add_u32_e32 v156, s44, v141
	v_add_u32_e32 v172, s81, v141
	ds_read_b128 v[144:147], v156
	ds_read_b128 v[148:151], v156 offset:1024
	ds_read_b128 v[152:155], v156 offset:2048
	ds_read_b128 v[156:159], v156 offset:3072
	ds_read_b128 v[160:163], v172
	ds_read_b128 v[164:167], v172 offset:1024
	ds_read_b128 v[168:171], v172 offset:2048
	ds_read_b128 v[172:175], v172 offset:3072
	s_add_i32 m0, s57, 0xc000
	ds_read_b128 v[176:179], v143
	ds_read_b128 v[180:183], v143 offset:1024
	ds_read_b128 v[184:187], v143 offset:2048
	ds_read_b128 v[188:191], v143 offset:3072
	ds_read_b128 v[192:195], v143 offset:4096
	ds_read_b128 v[196:199], v143 offset:5120
	ds_read_b128 v[200:203], v143 offset:6144
	ds_read_b128 v[204:207], v143 offset:7168
	global_load_lds_dwordx4 v136, s[88:89]
	s_add_i32 m0, s57, 0xe000
	s_nop 0
	global_load_lds_dwordx4 v138, s[88:89]
	s_waitcnt vmcnt(8)
	s_waitcnt lgkmcnt(0)
	s_barrier
	s_waitcnt lgkmcnt(0)
	v_mfma_f32_16x16x32_bf16 v[124:127], v[144:147], v[176:179], v[124:127]
	v_mfma_f32_16x16x32_bf16 v[120:123], v[152:155], v[176:179], v[120:123]
	v_mfma_f32_16x16x32_bf16 v[116:119], v[144:147], v[184:187], v[116:119]
	v_mfma_f32_16x16x32_bf16 v[112:115], v[152:155], v[184:187], v[112:115]
	v_mfma_f32_16x16x32_bf16 v[100:103], v[144:147], v[192:195], v[100:103]
	v_mfma_f32_16x16x32_bf16 v[96:99], v[152:155], v[192:195], v[96:99]
	v_mfma_f32_16x16x32_bf16 v[84:87], v[144:147], v[200:203], v[84:87]
	v_mfma_f32_16x16x32_bf16 v[80:83], v[152:155], v[200:203], v[80:83]
	v_mfma_f32_16x16x32_bf16 v[124:127], v[148:151], v[180:183], v[124:127]
	v_mfma_f32_16x16x32_bf16 v[120:123], v[156:159], v[180:183], v[120:123]
	v_mfma_f32_16x16x32_bf16 v[116:119], v[148:151], v[188:191], v[116:119]
	v_mfma_f32_16x16x32_bf16 v[112:115], v[156:159], v[188:191], v[112:115]
	v_mfma_f32_16x16x32_bf16 v[100:103], v[148:151], v[196:199], v[100:103]
	v_mfma_f32_16x16x32_bf16 v[96:99], v[156:159], v[196:199], v[96:99]
	v_mfma_f32_16x16x32_bf16 v[84:87], v[148:151], v[204:207], v[84:87]
	v_mfma_f32_16x16x32_bf16 v[80:83], v[156:159], v[204:207], v[80:83]
	v_mfma_f32_16x16x32_bf16 v[108:111], v[160:163], v[176:179], v[108:111]
	v_mfma_f32_16x16x32_bf16 v[104:107], v[168:171], v[176:179], v[104:107]
	v_mfma_f32_16x16x32_bf16 v[92:95], v[160:163], v[184:187], v[92:95]
	v_mfma_f32_16x16x32_bf16 v[88:91], v[168:171], v[184:187], v[88:91]
	v_mfma_f32_16x16x32_bf16 v[76:79], v[160:163], v[192:195], v[76:79]
	v_mfma_f32_16x16x32_bf16 v[72:75], v[168:171], v[192:195], v[72:75]
	v_mfma_f32_16x16x32_bf16 v[68:71], v[160:163], v[200:203], v[68:71]
	v_mfma_f32_16x16x32_bf16 v[64:67], v[168:171], v[200:203], v[64:67]
	v_mfma_f32_16x16x32_bf16 v[108:111], v[164:167], v[180:183], v[108:111]
	v_mfma_f32_16x16x32_bf16 v[104:107], v[172:175], v[180:183], v[104:107]
	v_mfma_f32_16x16x32_bf16 v[92:95], v[164:167], v[188:191], v[92:95]
	v_mfma_f32_16x16x32_bf16 v[88:91], v[172:175], v[188:191], v[88:91]
	v_mfma_f32_16x16x32_bf16 v[76:79], v[164:167], v[196:199], v[76:79]
	v_mfma_f32_16x16x32_bf16 v[72:75], v[172:175], v[196:199], v[72:75]
	v_mfma_f32_16x16x32_bf16 v[68:71], v[164:167], v[204:207], v[68:71]
	v_mfma_f32_16x16x32_bf16 v[64:67], v[172:175], v[204:207], v[64:67]
	s_barrier
	s_add_i32 s44, s44, s96
	s_mov_b32 m0, s44
	ds_read_b128 v[176:179], v143 offset:16384
	ds_read_b128 v[180:183], v143 offset:17408
	ds_read_b128 v[184:187], v143 offset:18432
	ds_read_b128 v[188:191], v143 offset:19456
	ds_read_b128 v[192:195], v143 offset:20480
	ds_read_b128 v[196:199], v143 offset:21504
	ds_read_b128 v[200:203], v143 offset:22528
	ds_read_b128 v[204:207], v143 offset:23552
	global_load_lds_dwordx4 v130, s[90:91]
	s_add_i32 m0, s44, 0x2000
	s_add_u32 s44, s90, 0x80000
	s_addc_u32 s45, s91, 0
	s_add_i32 s81, s81, s96
	global_load_lds_dwordx4 v134, s[90:91]
	s_mov_b32 m0, s81
	s_nop 0
	global_load_lds_dwordx4 v130, s[44:45]
	s_add_i32 m0, s81, 0x2000
	s_nop 0
	global_load_lds_dwordx4 v134, s[44:45]
	s_mov_b32 m0, s57
	s_nop 0
	global_load_lds_dwordx4 v128, s[22:23]
	s_mov_b32 m0, s97
	s_nop 0
	global_load_lds_dwordx4 v132, s[22:23]
	s_waitcnt vmcnt(8)
	s_waitcnt lgkmcnt(0)
	s_barrier
	s_waitcnt lgkmcnt(0)
	v_mfma_f32_16x16x32_bf16 v[60:63], v[144:147], v[176:179], v[60:63]
	v_mfma_f32_16x16x32_bf16 v[56:59], v[152:155], v[176:179], v[56:59]
	v_mfma_f32_16x16x32_bf16 v[52:55], v[144:147], v[184:187], v[52:55]
	v_mfma_f32_16x16x32_bf16 v[48:51], v[152:155], v[184:187], v[48:51]
	v_mfma_f32_16x16x32_bf16 v[36:39], v[144:147], v[192:195], v[36:39]
	v_mfma_f32_16x16x32_bf16 v[32:35], v[152:155], v[192:195], v[32:35]
	v_mfma_f32_16x16x32_bf16 v[20:23], v[144:147], v[200:203], v[20:23]
	v_mfma_f32_16x16x32_bf16 v[16:19], v[152:155], v[200:203], v[16:19]
	v_mfma_f32_16x16x32_bf16 v[60:63], v[148:151], v[180:183], v[60:63]
	v_mfma_f32_16x16x32_bf16 v[56:59], v[156:159], v[180:183], v[56:59]
	v_mfma_f32_16x16x32_bf16 v[52:55], v[148:151], v[188:191], v[52:55]
	v_mfma_f32_16x16x32_bf16 v[48:51], v[156:159], v[188:191], v[48:51]
	v_mfma_f32_16x16x32_bf16 v[36:39], v[148:151], v[196:199], v[36:39]
	v_mfma_f32_16x16x32_bf16 v[32:35], v[156:159], v[196:199], v[32:35]
	v_mfma_f32_16x16x32_bf16 v[20:23], v[148:151], v[204:207], v[20:23]
	v_mfma_f32_16x16x32_bf16 v[16:19], v[156:159], v[204:207], v[16:19]
	v_mfma_f32_16x16x32_bf16 v[44:47], v[160:163], v[176:179], v[44:47]
	v_mfma_f32_16x16x32_bf16 v[40:43], v[168:171], v[176:179], v[40:43]
	v_mfma_f32_16x16x32_bf16 v[28:31], v[160:163], v[184:187], v[28:31]
	v_mfma_f32_16x16x32_bf16 v[24:27], v[168:171], v[184:187], v[24:27]
	v_mfma_f32_16x16x32_bf16 v[12:15], v[160:163], v[192:195], v[12:15]
	v_mfma_f32_16x16x32_bf16 v[8:11], v[168:171], v[192:195], v[8:11]
	v_mfma_f32_16x16x32_bf16 v[4:7], v[160:163], v[200:203], v[4:7]
	v_mfma_f32_16x16x32_bf16 v[0:3], v[168:171], v[200:203], v[0:3]
	v_mfma_f32_16x16x32_bf16 v[44:47], v[164:167], v[180:183], v[44:47]
	v_mfma_f32_16x16x32_bf16 v[40:43], v[172:175], v[180:183], v[40:43]
	v_mfma_f32_16x16x32_bf16 v[28:31], v[164:167], v[188:191], v[28:31]
	v_mfma_f32_16x16x32_bf16 v[24:27], v[172:175], v[188:191], v[24:27]
	v_mfma_f32_16x16x32_bf16 v[12:15], v[164:167], v[196:199], v[12:15]
	v_mfma_f32_16x16x32_bf16 v[8:11], v[172:175], v[196:199], v[8:11]
	v_mfma_f32_16x16x32_bf16 v[4:7], v[164:167], v[204:207], v[4:7]
	v_mfma_f32_16x16x32_bf16 v[0:3], v[172:175], v[204:207], v[0:3]
	s_barrier
	s_add_i32 s44, 0, 0x18000
	s_add_i32 s45, 0, 0x1c000
	v_add_u32_e32 v156, s44, v141
	v_add_u32_e32 v172, s45, v141
	ds_read_b128 v[144:147], v156
	ds_read_b128 v[148:151], v156 offset:1024
	ds_read_b128 v[152:155], v156 offset:2048
	ds_read_b128 v[156:159], v156 offset:3072
	ds_read_b128 v[160:163], v172
	ds_read_b128 v[164:167], v172 offset:1024
	ds_read_b128 v[168:171], v172 offset:2048
	ds_read_b128 v[172:175], v172 offset:3072
	s_add_u32 s22, s22, 0x80000
	s_addc_u32 s23, s23, 0
	s_mov_b32 m0, s93
	ds_read_b128 v[176:179], v143 offset:32768
	ds_read_b128 v[180:183], v143 offset:33792
	ds_read_b128 v[184:187], v143 offset:34816
	ds_read_b128 v[188:191], v143 offset:35840
	ds_read_b128 v[192:195], v143 offset:36864
	ds_read_b128 v[196:199], v143 offset:37888
	ds_read_b128 v[200:203], v143 offset:38912
	ds_read_b128 v[204:207], v143 offset:39936
	global_load_lds_dwordx4 v128, s[22:23]
	s_mov_b32 m0, s94
	s_nop 0
	global_load_lds_dwordx4 v132, s[22:23]
	s_waitcnt vmcnt(8)
	s_waitcnt lgkmcnt(0)
	s_barrier
	s_waitcnt lgkmcnt(0)
	v_mfma_f32_16x16x32_bf16 v[124:127], v[144:147], v[176:179], v[124:127]
	v_mfma_f32_16x16x32_bf16 v[120:123], v[152:155], v[176:179], v[120:123]
	v_mfma_f32_16x16x32_bf16 v[116:119], v[144:147], v[184:187], v[116:119]
	v_mfma_f32_16x16x32_bf16 v[112:115], v[152:155], v[184:187], v[112:115]
	v_mfma_f32_16x16x32_bf16 v[100:103], v[144:147], v[192:195], v[100:103]
	v_mfma_f32_16x16x32_bf16 v[96:99], v[152:155], v[192:195], v[96:99]
	v_mfma_f32_16x16x32_bf16 v[84:87], v[144:147], v[200:203], v[84:87]
	v_mfma_f32_16x16x32_bf16 v[80:83], v[152:155], v[200:203], v[80:83]
	v_mfma_f32_16x16x32_bf16 v[124:127], v[148:151], v[180:183], v[124:127]
	v_mfma_f32_16x16x32_bf16 v[120:123], v[156:159], v[180:183], v[120:123]
	v_mfma_f32_16x16x32_bf16 v[116:119], v[148:151], v[188:191], v[116:119]
	v_mfma_f32_16x16x32_bf16 v[112:115], v[156:159], v[188:191], v[112:115]
	v_mfma_f32_16x16x32_bf16 v[100:103], v[148:151], v[196:199], v[100:103]
	v_mfma_f32_16x16x32_bf16 v[96:99], v[156:159], v[196:199], v[96:99]
	v_mfma_f32_16x16x32_bf16 v[84:87], v[148:151], v[204:207], v[84:87]
	v_mfma_f32_16x16x32_bf16 v[80:83], v[156:159], v[204:207], v[80:83]
	v_mfma_f32_16x16x32_bf16 v[108:111], v[160:163], v[176:179], v[108:111]
	v_mfma_f32_16x16x32_bf16 v[104:107], v[168:171], v[176:179], v[104:107]
	v_mfma_f32_16x16x32_bf16 v[92:95], v[160:163], v[184:187], v[92:95]
	v_mfma_f32_16x16x32_bf16 v[88:91], v[168:171], v[184:187], v[88:91]
	v_mfma_f32_16x16x32_bf16 v[76:79], v[160:163], v[192:195], v[76:79]
	v_mfma_f32_16x16x32_bf16 v[72:75], v[168:171], v[192:195], v[72:75]
	v_mfma_f32_16x16x32_bf16 v[68:71], v[160:163], v[200:203], v[68:71]
	v_mfma_f32_16x16x32_bf16 v[64:67], v[168:171], v[200:203], v[64:67]
	v_mfma_f32_16x16x32_bf16 v[108:111], v[164:167], v[180:183], v[108:111]
	v_mfma_f32_16x16x32_bf16 v[104:107], v[172:175], v[180:183], v[104:107]
	v_mfma_f32_16x16x32_bf16 v[92:95], v[164:167], v[188:191], v[92:95]
	v_mfma_f32_16x16x32_bf16 v[88:91], v[172:175], v[188:191], v[88:91]
	v_mfma_f32_16x16x32_bf16 v[76:79], v[164:167], v[196:199], v[76:79]
	v_mfma_f32_16x16x32_bf16 v[72:75], v[172:175], v[196:199], v[72:75]
	v_mfma_f32_16x16x32_bf16 v[68:71], v[164:167], v[204:207], v[68:71]
	v_mfma_f32_16x16x32_bf16 v[64:67], v[172:175], v[204:207], v[64:67]
	s_barrier
	s_add_i32 s22, s44, s96
	s_add_i32 m0, s22, 0xffffff80
	ds_read_b128 v[176:179], v143 offset:49152
	ds_read_b128 v[180:183], v143 offset:50176
	ds_read_b128 v[184:187], v143 offset:51200
	ds_read_b128 v[188:191], v143 offset:52224
	ds_read_b128 v[192:195], v143 offset:53248
	ds_read_b128 v[196:199], v143 offset:54272
	ds_read_b128 v[200:203], v143 offset:55296
	ds_read_b128 v[204:207], v143 offset:56320
	global_load_lds_dwordx4 v130, s[90:91] offset:128
	s_add_i32 m0, s22, 0x1f80
	s_add_u32 s22, s90, 0x80080
	s_addc_u32 s23, s91, 0
	s_add_i32 s44, s45, s96
	global_load_lds_dwordx4 v134, s[90:91] offset:128
	s_mov_b32 m0, s44
	s_nop 0
	global_load_lds_dwordx4 v130, s[22:23]
	s_add_i32 m0, s44, 0x2000
	s_nop 0
	global_load_lds_dwordx4 v134, s[22:23]
	s_add_u32 s22, s88, 0xfff80080
	s_addc_u32 s23, s89, -1
	s_cmp_eq_u32 s43, 28
	s_cselect_b32 s23, s30, s23
	s_cselect_b32 s22, s31, s22
	s_add_i32 m0, s92, 0xffffff80
	s_nop 0
	global_load_lds_dwordx4 v128, s[22:23] offset:128
	s_add_i32 m0, s6, 0xffffff80
	s_nop 0
	global_load_lds_dwordx4 v132, s[22:23] offset:128
	s_waitcnt vmcnt(8)
	s_waitcnt lgkmcnt(0)
	s_barrier
	s_waitcnt lgkmcnt(0)
	v_mfma_f32_16x16x32_bf16 v[60:63], v[144:147], v[176:179], v[60:63]
	v_mfma_f32_16x16x32_bf16 v[56:59], v[152:155], v[176:179], v[56:59]
	v_mfma_f32_16x16x32_bf16 v[52:55], v[144:147], v[184:187], v[52:55]
	v_mfma_f32_16x16x32_bf16 v[48:51], v[152:155], v[184:187], v[48:51]
	v_mfma_f32_16x16x32_bf16 v[36:39], v[144:147], v[192:195], v[36:39]
	v_mfma_f32_16x16x32_bf16 v[32:35], v[152:155], v[192:195], v[32:35]
	v_mfma_f32_16x16x32_bf16 v[20:23], v[144:147], v[200:203], v[20:23]
	v_mfma_f32_16x16x32_bf16 v[16:19], v[152:155], v[200:203], v[16:19]
	v_mfma_f32_16x16x32_bf16 v[60:63], v[148:151], v[180:183], v[60:63]
	v_mfma_f32_16x16x32_bf16 v[56:59], v[156:159], v[180:183], v[56:59]
	v_mfma_f32_16x16x32_bf16 v[52:55], v[148:151], v[188:191], v[52:55]
	v_mfma_f32_16x16x32_bf16 v[48:51], v[156:159], v[188:191], v[48:51]
	v_mfma_f32_16x16x32_bf16 v[36:39], v[148:151], v[196:199], v[36:39]
	v_mfma_f32_16x16x32_bf16 v[32:35], v[156:159], v[196:199], v[32:35]
	v_mfma_f32_16x16x32_bf16 v[20:23], v[148:151], v[204:207], v[20:23]
	v_mfma_f32_16x16x32_bf16 v[16:19], v[156:159], v[204:207], v[16:19]
	v_mfma_f32_16x16x32_bf16 v[44:47], v[160:163], v[176:179], v[44:47]
	v_mfma_f32_16x16x32_bf16 v[40:43], v[168:171], v[176:179], v[40:43]
	v_mfma_f32_16x16x32_bf16 v[28:31], v[160:163], v[184:187], v[28:31]
	v_mfma_f32_16x16x32_bf16 v[24:27], v[168:171], v[184:187], v[24:27]
	v_mfma_f32_16x16x32_bf16 v[12:15], v[160:163], v[192:195], v[12:15]
	v_mfma_f32_16x16x32_bf16 v[8:11], v[168:171], v[192:195], v[8:11]
	v_mfma_f32_16x16x32_bf16 v[4:7], v[160:163], v[200:203], v[4:7]
	v_mfma_f32_16x16x32_bf16 v[0:3], v[168:171], v[200:203], v[0:3]
	v_mfma_f32_16x16x32_bf16 v[44:47], v[164:167], v[180:183], v[44:47]
	v_mfma_f32_16x16x32_bf16 v[40:43], v[172:175], v[180:183], v[40:43]
	v_mfma_f32_16x16x32_bf16 v[28:31], v[164:167], v[188:191], v[28:31]
	v_mfma_f32_16x16x32_bf16 v[24:27], v[172:175], v[188:191], v[24:27]
	v_mfma_f32_16x16x32_bf16 v[12:15], v[164:167], v[196:199], v[12:15]
	v_mfma_f32_16x16x32_bf16 v[8:11], v[172:175], v[196:199], v[8:11]
	v_mfma_f32_16x16x32_bf16 v[4:7], v[164:167], v[204:207], v[4:7]
	v_mfma_f32_16x16x32_bf16 v[0:3], v[172:175], v[204:207], v[0:3]
	s_barrier
	s_add_i32 s43, s43, 2
	s_add_u32 s88, s88, 0x100
	s_addc_u32 s89, s89, 0
	s_add_u32 s41, s41, 0x100
	s_addc_u32 s42, s42, 0
	s_cmp_gt_u32 s43, 29
	s_cbranch_scc0 .LBB0_631
	s_cmp_eq_u32 s40, 0
	s_cselect_b64 s[30:31], -1, 0
	s_cmp_lg_u32 s40, 0
	s_mov_b64 s[38:39], -1
	s_cbranch_scc0 .LBB0_634
	s_lshl_b32 s22, s80, 8
	s_or_b32 s22, s22, s53
	s_ashr_i32 s22, s22, 6
	s_mov_b64 s[38:39], 0

.LBB0_1259:
	s_add_u32 s22, s92, s76
	s_addc_u32 s23, s93, s77
	s_add_u32 s80, s96, s76
	s_addc_u32 s81, s97, s77
	s_cmp_eq_u32 s44, 0
	s_cselect_b32 s23, s15, s23
	s_cselect_b32 s22, s91, s22
	s_cselect_b32 vcc_hi, s89, s81
	s_cselect_b32 vcc_lo, s8, s80
	s_add_i32 s80, 0, 0x10000
	v_add_u32_e32 v141, s80, v138
	s_add_i32 s83, 0, 0x14000
	ds_read_b128 v[142:145], v141
	ds_read_b128 v[146:149], v141 offset:1024
	ds_read_b128 v[150:153], v141 offset:2048
	ds_read_b128 v[154:157], v141 offset:3072
	v_add_u32_e32 v141, s83, v138
	ds_read_b128 v[158:161], v141
	ds_read_b128 v[162:165], v141 offset:1024
	ds_read_b128 v[166:169], v141 offset:2048
	ds_read_b128 v[170:173], v141 offset:3072
	s_add_i32 m0, s45, 0xc000
	ds_read_b128 v[174:177], v140
	ds_read_b128 v[178:181], v140 offset:1024
	ds_read_b128 v[182:185], v140 offset:2048
	ds_read_b128 v[186:189], v140 offset:3072
	ds_read_b128 v[190:193], v140 offset:4096
	ds_read_b128 v[194:197], v140 offset:5120
	ds_read_b128 v[198:201], v140 offset:6144
	ds_read_b128 v[202:205], v140 offset:7168
	global_load_lds_dwordx4 v136, s[92:93]
	s_add_i32 m0, s45, 0xe000
	s_nop 0
	global_load_lds_dwordx4 v134, s[92:93]
	s_waitcnt vmcnt(8)
	s_waitcnt lgkmcnt(0)
	s_barrier
	s_waitcnt lgkmcnt(0)
	v_mfma_f32_16x16x32_bf16 v[124:127], v[142:145], v[174:177], v[124:127]
	v_mfma_f32_16x16x32_bf16 v[120:123], v[150:153], v[174:177], v[120:123]
	v_mfma_f32_16x16x32_bf16 v[108:111], v[142:145], v[182:185], v[108:111]
	v_mfma_f32_16x16x32_bf16 v[104:107], v[150:153], v[182:185], v[104:107]
	v_mfma_f32_16x16x32_bf16 v[92:95], v[142:145], v[190:193], v[92:95]
	v_mfma_f32_16x16x32_bf16 v[88:91], v[150:153], v[190:193], v[88:91]
	v_mfma_f32_16x16x32_bf16 v[76:79], v[142:145], v[198:201], v[76:79]
	v_mfma_f32_16x16x32_bf16 v[72:75], v[150:153], v[198:201], v[72:75]
	v_mfma_f32_16x16x32_bf16 v[124:127], v[146:149], v[178:181], v[124:127]
	v_mfma_f32_16x16x32_bf16 v[120:123], v[154:157], v[178:181], v[120:123]
	v_mfma_f32_16x16x32_bf16 v[108:111], v[146:149], v[186:189], v[108:111]
	v_mfma_f32_16x16x32_bf16 v[104:107], v[154:157], v[186:189], v[104:107]
	v_mfma_f32_16x16x32_bf16 v[92:95], v[146:149], v[194:197], v[92:95]
	v_mfma_f32_16x16x32_bf16 v[88:91], v[154:157], v[194:197], v[88:91]
	v_mfma_f32_16x16x32_bf16 v[76:79], v[146:149], v[202:205], v[76:79]
	v_mfma_f32_16x16x32_bf16 v[72:75], v[154:157], v[202:205], v[72:75]
	v_mfma_f32_16x16x32_bf16 v[116:119], v[158:161], v[174:177], v[116:119]
	v_mfma_f32_16x16x32_bf16 v[112:115], v[166:169], v[174:177], v[112:115]
	v_mfma_f32_16x16x32_bf16 v[100:103], v[158:161], v[182:185], v[100:103]
	v_mfma_f32_16x16x32_bf16 v[96:99], v[166:169], v[182:185], v[96:99]
	v_mfma_f32_16x16x32_bf16 v[84:87], v[158:161], v[190:193], v[84:87]
	v_mfma_f32_16x16x32_bf16 v[80:83], v[166:169], v[190:193], v[80:83]
	v_mfma_f32_16x16x32_bf16 v[68:71], v[158:161], v[198:201], v[68:71]
	v_mfma_f32_16x16x32_bf16 v[64:67], v[166:169], v[198:201], v[64:67]
	v_mfma_f32_16x16x32_bf16 v[116:119], v[162:165], v[178:181], v[116:119]
	v_mfma_f32_16x16x32_bf16 v[112:115], v[170:173], v[178:181], v[112:115]
	v_mfma_f32_16x16x32_bf16 v[100:103], v[162:165], v[186:189], v[100:103]
	v_mfma_f32_16x16x32_bf16 v[96:99], v[170:173], v[186:189], v[96:99]
	v_mfma_f32_16x16x32_bf16 v[84:87], v[162:165], v[194:197], v[84:87]
	v_mfma_f32_16x16x32_bf16 v[80:83], v[170:173], v[194:197], v[80:83]
	v_mfma_f32_16x16x32_bf16 v[68:71], v[162:165], v[202:205], v[68:71]
	v_mfma_f32_16x16x32_bf16 v[64:67], v[170:173], v[202:205], v[64:67]
	s_barrier
	s_add_i32 s80, s80, s43
	s_mov_b32 m0, s80
	ds_read_b128 v[174:177], v140 offset:16384
	ds_read_b128 v[178:181], v140 offset:17408
	ds_read_b128 v[182:185], v140 offset:18432
	ds_read_b128 v[186:189], v140 offset:19456
	ds_read_b128 v[190:193], v140 offset:20480
	ds_read_b128 v[194:197], v140 offset:21504
	ds_read_b128 v[198:201], v140 offset:22528
	ds_read_b128 v[202:205], v140 offset:23552
	global_load_lds_dwordx4 v208, vcc
	s_add_i32 m0, s80, 0x2000
	s_add_u32 s80, vcc_lo, 0x80000
	s_addc_u32 s81, vcc_hi, 0
	s_add_i32 s83, s83, s43
	global_load_lds_dwordx4 v128, vcc
	s_mov_b32 m0, s83
	s_nop 0
	global_load_lds_dwordx4 v208, s[80:81]
	s_add_i32 m0, s83, 0x2000
	s_nop 0
	global_load_lds_dwordx4 v128, s[80:81]
	s_mov_b32 m0, s45
	s_nop 0
	global_load_lds_dwordx4 v208, s[22:23]
	s_mov_b32 m0, s52
	s_nop 0
	global_load_lds_dwordx4 v128, s[22:23]
	s_waitcnt vmcnt(8)
	s_waitcnt lgkmcnt(0)
	s_barrier
	s_waitcnt lgkmcnt(0)
	v_mfma_f32_16x16x32_bf16 v[60:63], v[142:145], v[174:177], v[60:63]
	v_mfma_f32_16x16x32_bf16 v[56:59], v[150:153], v[174:177], v[56:59]
	v_mfma_f32_16x16x32_bf16 v[44:47], v[142:145], v[182:185], v[44:47]
	v_mfma_f32_16x16x32_bf16 v[40:43], v[150:153], v[182:185], v[40:43]
	v_mfma_f32_16x16x32_bf16 v[28:31], v[142:145], v[190:193], v[28:31]
	v_mfma_f32_16x16x32_bf16 v[24:27], v[150:153], v[190:193], v[24:27]
	v_mfma_f32_16x16x32_bf16 v[12:15], v[142:145], v[198:201], v[12:15]
	v_mfma_f32_16x16x32_bf16 v[8:11], v[150:153], v[198:201], v[8:11]
	v_mfma_f32_16x16x32_bf16 v[60:63], v[146:149], v[178:181], v[60:63]
	v_mfma_f32_16x16x32_bf16 v[56:59], v[154:157], v[178:181], v[56:59]
	v_mfma_f32_16x16x32_bf16 v[44:47], v[146:149], v[186:189], v[44:47]
	v_mfma_f32_16x16x32_bf16 v[40:43], v[154:157], v[186:189], v[40:43]
	v_mfma_f32_16x16x32_bf16 v[28:31], v[146:149], v[194:197], v[28:31]
	v_mfma_f32_16x16x32_bf16 v[24:27], v[154:157], v[194:197], v[24:27]
	v_mfma_f32_16x16x32_bf16 v[12:15], v[146:149], v[202:205], v[12:15]
	v_mfma_f32_16x16x32_bf16 v[8:11], v[154:157], v[202:205], v[8:11]
	v_mfma_f32_16x16x32_bf16 v[52:55], v[158:161], v[174:177], v[52:55]
	v_mfma_f32_16x16x32_bf16 v[48:51], v[166:169], v[174:177], v[48:51]
	v_mfma_f32_16x16x32_bf16 v[36:39], v[158:161], v[182:185], v[36:39]
	v_mfma_f32_16x16x32_bf16 v[32:35], v[166:169], v[182:185], v[32:35]
	v_mfma_f32_16x16x32_bf16 v[20:23], v[158:161], v[190:193], v[20:23]
	v_mfma_f32_16x16x32_bf16 v[16:19], v[166:169], v[190:193], v[16:19]
	v_mfma_f32_16x16x32_bf16 v[4:7], v[158:161], v[198:201], v[4:7]
	v_mfma_f32_16x16x32_bf16 v[0:3], v[166:169], v[198:201], v[0:3]
	v_mfma_f32_16x16x32_bf16 v[52:55], v[162:165], v[178:181], v[52:55]
	v_mfma_f32_16x16x32_bf16 v[48:51], v[170:173], v[178:181], v[48:51]
	v_mfma_f32_16x16x32_bf16 v[36:39], v[162:165], v[186:189], v[36:39]
	v_mfma_f32_16x16x32_bf16 v[32:35], v[170:173], v[186:189], v[32:35]
	v_mfma_f32_16x16x32_bf16 v[20:23], v[162:165], v[194:197], v[20:23]
	v_mfma_f32_16x16x32_bf16 v[16:19], v[170:173], v[194:197], v[16:19]
	v_mfma_f32_16x16x32_bf16 v[4:7], v[162:165], v[202:205], v[4:7]
	v_mfma_f32_16x16x32_bf16 v[0:3], v[170:173], v[202:205], v[0:3]
	s_barrier
	s_add_i32 s80, 0, 0x18000
	v_add_u32_e32 v141, s80, v138
	s_add_i32 s81, 0, 0x1c000
	ds_read_b128 v[142:145], v141
	ds_read_b128 v[146:149], v141 offset:1024
	ds_read_b128 v[150:153], v141 offset:2048
	ds_read_b128 v[154:157], v141 offset:3072
	v_add_u32_e32 v141, s81, v138
	ds_read_b128 v[158:161], v141
	ds_read_b128 v[162:165], v141 offset:1024
	ds_read_b128 v[166:169], v141 offset:2048
	ds_read_b128 v[170:173], v141 offset:3072
	s_add_u32 s22, s22, 0x80000
	s_addc_u32 s23, s23, 0
	s_mov_b32 m0, s53
	ds_read_b128 v[174:177], v140 offset:32768
	ds_read_b128 v[178:181], v140 offset:33792
	ds_read_b128 v[182:185], v140 offset:34816
	ds_read_b128 v[186:189], v140 offset:35840
	ds_read_b128 v[190:193], v140 offset:36864
	ds_read_b128 v[194:197], v140 offset:37888
	ds_read_b128 v[198:201], v140 offset:38912
	ds_read_b128 v[202:205], v140 offset:39936
	global_load_lds_dwordx4 v208, s[22:23]
	s_mov_b32 m0, s85
	s_nop 0
	global_load_lds_dwordx4 v128, s[22:23]
	s_waitcnt vmcnt(8)
	s_waitcnt lgkmcnt(0)
	s_barrier
	s_waitcnt lgkmcnt(0)
	v_mfma_f32_16x16x32_bf16 v[124:127], v[142:145], v[174:177], v[124:127]
	v_mfma_f32_16x16x32_bf16 v[120:123], v[150:153], v[174:177], v[120:123]
	v_mfma_f32_16x16x32_bf16 v[108:111], v[142:145], v[182:185], v[108:111]
	v_mfma_f32_16x16x32_bf16 v[104:107], v[150:153], v[182:185], v[104:107]
	v_mfma_f32_16x16x32_bf16 v[92:95], v[142:145], v[190:193], v[92:95]
	v_mfma_f32_16x16x32_bf16 v[88:91], v[150:153], v[190:193], v[88:91]
	v_mfma_f32_16x16x32_bf16 v[76:79], v[142:145], v[198:201], v[76:79]
	v_mfma_f32_16x16x32_bf16 v[72:75], v[150:153], v[198:201], v[72:75]
	v_mfma_f32_16x16x32_bf16 v[124:127], v[146:149], v[178:181], v[124:127]
	v_mfma_f32_16x16x32_bf16 v[120:123], v[154:157], v[178:181], v[120:123]
	v_mfma_f32_16x16x32_bf16 v[108:111], v[146:149], v[186:189], v[108:111]
	v_mfma_f32_16x16x32_bf16 v[104:107], v[154:157], v[186:189], v[104:107]
	v_mfma_f32_16x16x32_bf16 v[92:95], v[146:149], v[194:197], v[92:95]
	v_mfma_f32_16x16x32_bf16 v[88:91], v[154:157], v[194:197], v[88:91]
	v_mfma_f32_16x16x32_bf16 v[76:79], v[146:149], v[202:205], v[76:79]
	v_mfma_f32_16x16x32_bf16 v[72:75], v[154:157], v[202:205], v[72:75]
	v_mfma_f32_16x16x32_bf16 v[116:119], v[158:161], v[174:177], v[116:119]
	v_mfma_f32_16x16x32_bf16 v[112:115], v[166:169], v[174:177], v[112:115]
	v_mfma_f32_16x16x32_bf16 v[100:103], v[158:161], v[182:185], v[100:103]
	v_mfma_f32_16x16x32_bf16 v[96:99], v[166:169], v[182:185], v[96:99]
	v_mfma_f32_16x16x32_bf16 v[84:87], v[158:161], v[190:193], v[84:87]
	v_mfma_f32_16x16x32_bf16 v[80:83], v[166:169], v[190:193], v[80:83]
	v_mfma_f32_16x16x32_bf16 v[68:71], v[158:161], v[198:201], v[68:71]
	v_mfma_f32_16x16x32_bf16 v[64:67], v[166:169], v[198:201], v[64:67]
	v_mfma_f32_16x16x32_bf16 v[116:119], v[162:165], v[178:181], v[116:119]
	v_mfma_f32_16x16x32_bf16 v[112:115], v[170:173], v[178:181], v[112:115]
	v_mfma_f32_16x16x32_bf16 v[100:103], v[162:165], v[186:189], v[100:103]
	v_mfma_f32_16x16x32_bf16 v[96:99], v[170:173], v[186:189], v[96:99]
	v_mfma_f32_16x16x32_bf16 v[84:87], v[162:165], v[194:197], v[84:87]
	v_mfma_f32_16x16x32_bf16 v[80:83], v[170:173], v[194:197], v[80:83]
	v_mfma_f32_16x16x32_bf16 v[68:71], v[162:165], v[202:205], v[68:71]
	v_mfma_f32_16x16x32_bf16 v[64:67], v[170:173], v[202:205], v[64:67]
	s_barrier
	s_add_i32 s22, s80, s43
	s_add_i32 m0, s22, 0xffffff80
	ds_read_b128 v[174:177], v140 offset:49152
	ds_read_b128 v[178:181], v140 offset:50176
	ds_read_b128 v[182:185], v140 offset:51200
	ds_read_b128 v[186:189], v140 offset:52224
	ds_read_b128 v[190:193], v140 offset:53248
	ds_read_b128 v[194:197], v140 offset:54272
	ds_read_b128 v[198:201], v140 offset:55296
	ds_read_b128 v[202:205], v140 offset:56320
	global_load_lds_dwordx4 v208, vcc offset:128
	s_add_i32 m0, s22, 0x1f80
	s_add_u32 s22, vcc_lo, 0x80080
	s_addc_u32 s23, vcc_hi, 0
	s_add_i32 s80, s81, s43
	global_load_lds_dwordx4 v128, vcc offset:128
	s_mov_b32 m0, s80
	s_nop 0
	global_load_lds_dwordx4 v208, s[22:23]
	s_add_i32 m0, s80, 0x2000
	s_nop 0
	global_load_lds_dwordx4 v128, s[22:23]
	s_add_u32 s22, s92, s76
	s_addc_u32 s23, s93, s77
	s_cmp_eq_u32 s44, 0
	s_cselect_b32 s23, s15, s23
	s_cselect_b32 s22, s91, s22
	s_add_i32 m0, s9, 0xffffff80
	s_nop 0
	global_load_lds_dwordx4 v208, s[22:23] offset:128
	s_add_i32 m0, s12, 0xffffff80
	s_nop 0
	global_load_lds_dwordx4 v128, s[22:23] offset:128
	s_waitcnt vmcnt(8)
	s_waitcnt lgkmcnt(0)
	s_barrier
	s_waitcnt lgkmcnt(0)
	v_mfma_f32_16x16x32_bf16 v[60:63], v[142:145], v[174:177], v[60:63]
	v_mfma_f32_16x16x32_bf16 v[56:59], v[150:153], v[174:177], v[56:59]
	v_mfma_f32_16x16x32_bf16 v[44:47], v[142:145], v[182:185], v[44:47]
	v_mfma_f32_16x16x32_bf16 v[40:43], v[150:153], v[182:185], v[40:43]
	v_mfma_f32_16x16x32_bf16 v[28:31], v[142:145], v[190:193], v[28:31]
	v_mfma_f32_16x16x32_bf16 v[24:27], v[150:153], v[190:193], v[24:27]
	v_mfma_f32_16x16x32_bf16 v[12:15], v[142:145], v[198:201], v[12:15]
	v_mfma_f32_16x16x32_bf16 v[8:11], v[150:153], v[198:201], v[8:11]
	v_mfma_f32_16x16x32_bf16 v[60:63], v[146:149], v[178:181], v[60:63]
	v_mfma_f32_16x16x32_bf16 v[56:59], v[154:157], v[178:181], v[56:59]
	v_mfma_f32_16x16x32_bf16 v[44:47], v[146:149], v[186:189], v[44:47]
	v_mfma_f32_16x16x32_bf16 v[40:43], v[154:157], v[186:189], v[40:43]
	v_mfma_f32_16x16x32_bf16 v[28:31], v[146:149], v[194:197], v[28:31]
	v_mfma_f32_16x16x32_bf16 v[24:27], v[154:157], v[194:197], v[24:27]
	v_mfma_f32_16x16x32_bf16 v[12:15], v[146:149], v[202:205], v[12:15]
	v_mfma_f32_16x16x32_bf16 v[8:11], v[154:157], v[202:205], v[8:11]
	v_mfma_f32_16x16x32_bf16 v[52:55], v[158:161], v[174:177], v[52:55]
	v_mfma_f32_16x16x32_bf16 v[48:51], v[166:169], v[174:177], v[48:51]
	v_mfma_f32_16x16x32_bf16 v[36:39], v[158:161], v[182:185], v[36:39]
	v_mfma_f32_16x16x32_bf16 v[32:35], v[166:169], v[182:185], v[32:35]
	v_mfma_f32_16x16x32_bf16 v[20:23], v[158:161], v[190:193], v[20:23]
	v_mfma_f32_16x16x32_bf16 v[16:19], v[166:169], v[190:193], v[16:19]
	v_mfma_f32_16x16x32_bf16 v[4:7], v[158:161], v[198:201], v[4:7]
	v_mfma_f32_16x16x32_bf16 v[0:3], v[166:169], v[198:201], v[0:3]
	v_mfma_f32_16x16x32_bf16 v[52:55], v[162:165], v[178:181], v[52:55]
	v_mfma_f32_16x16x32_bf16 v[48:51], v[170:173], v[178:181], v[48:51]
	v_mfma_f32_16x16x32_bf16 v[36:39], v[162:165], v[186:189], v[36:39]
	v_mfma_f32_16x16x32_bf16 v[32:35], v[170:173], v[186:189], v[32:35]
	v_mfma_f32_16x16x32_bf16 v[20:23], v[162:165], v[194:197], v[20:23]
	v_mfma_f32_16x16x32_bf16 v[16:19], v[170:173], v[194:197], v[16:19]
	v_mfma_f32_16x16x32_bf16 v[4:7], v[162:165], v[202:205], v[4:7]
	v_mfma_f32_16x16x32_bf16 v[0:3], v[170:173], v[202:205], v[0:3]
	s_barrier
	s_addk_i32 s44, 0x200
	s_add_u32 s76, s76, 0x100
	s_addc_u32 s77, s77, 0
	s_add_i32 s22, s82, 2
	v_lshl_add_u64 v[136:137], v[136:137], 0, s[58:59]
	s_cmp_gt_u32 s82, 29
	v_lshl_add_u64 v[134:135], v[134:135], 0, s[58:59]
	s_cbranch_scc1 .LBB0_1261
	s_mov_b32 s82, s22
	s_branch .LBB0_1257
